# grid barrier flat release: members poll the top generation word directly, no per-XCD release atomic, last leader overlaps its L1 invalidate with the release atomic
# speedup vs baseline: 1.0243x; 1.0062x over previous
.LBB0_1132:
	s_or_b64 exec, exec, s[8:9]
	v_cvt_f32_u32_e32 v5, v3
	s_waitcnt vmcnt(0)
	v_readfirstlane_b32 s6, v4
	v_sub_u32_e32 v4, 0, v3
	v_rcp_iflag_f32_e32 v5, v5
	v_add_u32_e32 v6, s6, v0
	v_mul_f32_e32 v5, 0x4f7ffffe, v5
	v_cvt_u32_f32_e32 v5, v5
	v_mul_lo_u32 v0, v4, v5
	v_mul_hi_u32 v0, v5, v0
	v_add_u32_e32 v0, v5, v0
	v_mul_hi_u32 v0, v6, v0
	v_mul_lo_u32 v4, v0, v3
	v_sub_u32_e32 v4, v6, v4
	v_add_u32_e32 v5, 1, v0
	v_cmp_ge_u32_e32 vcc, v4, v3
	s_nop 1
	v_cndmask_b32_e32 v0, v0, v5, vcc
	v_sub_u32_e32 v5, v4, v3
	v_cndmask_b32_e32 v4, v4, v5, vcc
	v_add_u32_e32 v5, 1, v0
	v_cmp_ge_u32_e32 vcc, v4, v3
	v_add_u32_e32 v4, 1, v6
	s_nop 0
	v_cndmask_b32_e32 v0, v0, v5, vcc
	v_mul_lo_u32 v5, v3, v0
	v_add_u32_e32 v3, v5, v3
	v_cmp_ne_u32_e32 vcc, v4, v3
	s_and_saveexec_b64 s[6:7], vcc
	s_xor_b64 s[6:7], exec, s[6:7]
	s_movk_i32 s46, 0x1000
	s_cbranch_execz .LBB0_1146
	s_waitcnt lgkmcnt(0)
	buffer_inv sc1
	s_add_u32 s12, s2, 0x83500
	s_addc_u32 s13, s3, 0
	global_load_dword v2, v1, s[12:13] sc1
	s_waitcnt vmcnt(0)
	v_cmp_eq_u32_e32 vcc, v2, v0
	s_and_saveexec_b64 s[8:9], vcc
	s_cbranch_execz .LBB0_1145
	s_add_u32 s10, s2, 0x80200
	s_addc_u32 s11, s3, 0
	s_mov_b32 s24, 1
	s_mov_b64 s[14:15], 0
	s_branch .LBB0_1136

.LBB0_1163:
	s_or_b64 exec, exec, s[2:3]
	s_mov_b64 s[2:3], exec
	v_mbcnt_lo_u32_b32 v0, s2, 0
	v_mbcnt_hi_u32_b32 v0, s3, v0
	v_cmp_eq_u32_e32 vcc, 0, v0
	s_cmp_lg_u32 s24, 0
	s_cbranch_scc1 .Lbar_inv_done
	buffer_inv sc1
.Lbar_inv_done:
	s_and_saveexec_b64 s[6:7], vcc
	s_getpc_b64 s[98:99]
